# MLA attention loop hand-scheduled: persistent C-init block replaces per-tile accumulator init, streamed exp/sum/fp8 pack, SGPR-base prefetch loads
# speedup vs baseline: 1.0121x; 1.0121x over previous
; __device__ __forceinline__ void finishSM9(f32x16& p0, f32x16& p1, float alpha, float& l_reg, v8i32& p8) {
; #pragma unroll
;   for (int r = 0; r < 16; ++r) { p0[r] = __builtin_amdgcn_exp2f(p0[r]); p1[r] = __builtin_amdgcn_exp2f(p1[r]); }
;   float ps = 0;
; #pragma unroll
;   for (int r = 0; r < 16; ++r) ps += p0[r];
; #pragma unroll
;   for (int r = 0; r < 16; ++r) ps += p1[r];
;   { auto rr = __builtin_amdgcn_permlane32_swap(__float_as_uint(ps), __float_as_uint(ps), false, false);
;     ps = __uint_as_float(rr[0]) + __uint_as_float(rr[1]); }
;   l_reg = l_reg * alpha + ps;
; #pragma unroll
;   for (int g = 0; g < 4; ++g) {
;     int w = __builtin_amdgcn_cvt_pk_fp8_f32(p0[4 * g], p0[4 * g + 1], 0, false); p8[g] = __builtin_amdgcn_cvt_pk_fp8_f32(p0[4 * g + 2], p0[4 * g + 3], w, true);
;     int u = __builtin_amdgcn_cvt_pk_fp8_f32(p1[4 * g], p1[4 * g + 1], 0, false); p8[4 + g] = __builtin_amdgcn_cvt_pk_fp8_f32(p1[4 * g + 2], p1[4 * g + 3], u, true); }
; }
; __device__ __forceinline__ void pv8(f32x16* o, const char* Vt, const v8i32 p8, int r32, int hi) {
;   const int sw = (r32 >> 2) & 3, a0 = r32 * 64 + (((hi * 2) ^ sw) << 4), a1 = r32 * 64 + (((hi * 2 + 1) ^ sw) << 4);
; #pragma unroll
;   for (int d0 = 0; d0 < 4; ++d0) {
;     const v8i32 vf = cat8(*reinterpret_cast<const v4i32*>(Vt + d0 * 2048 + a0), *reinterpret_cast<const v4i32*>(Vt + d0 * 2048 + a1));
;     o[d0] = __builtin_amdgcn_mfma_scale_f32_32x32x64_f8f6f4(p8, vf, o[d0], 0, 0, 0, 127, 0, 127); }
; }
; __device__ __forceinline__ void qkt9(f32x16& p0, f32x16& p1, const char* Kn, const char* Kr, const v8i32* qf, const float init, int r32, int hi) {
; #pragma unroll
;   for (int r = 0; r < 16; ++r) { p0[r] = init; p1[r] = init; }
; #pragma unroll
;   for (int s = 0; s < 2; ++s) { const int c0 = s * 4 + hi * 2;
;     const v8i32 a0 = cat8(*reinterpret_cast<const v4i32*>(Kn + KN8SW(r32, c0)), *reinterpret_cast<const v4i32*>(Kn + KN8SW(r32, c0 + 1)));
; __device__ __forceinline__ void attn_unit7(const unsigned char* __restrict__ Q8, int ldq, const unsigned char* __restrict__ Kn8, int ldk, const unsigned char* __restrict__ Kr8, ...
;     ...
;   for (int j = 1; j + 1 < NT; j += 2) {
;     SLOAD();
;     qkt9(pB0, pB1, Kn_lds + 8192, Kr_lds + 4096, qf, 7.0f - m_reg, r32, hi);
;     finishSM9(pA0, pA1, alA, l_reg, p8);
;     pv8(o, Vt_lds, p8, r32, hi); partialSM9(pB0, pB1, m_reg, alB, thr_raw);
.LBB0_1320:
	s_or_b64 exec, exec, s[20:21]
	v_and_b32_e32 v0, 0x3fffffc0, v12
	s_mov_b32 s20, 0x60000
	v_lshl_add_u32 v187, v0, 2, 0
	v_add3_u32 v178, v13, v14, s20
	v_add_u32_e32 v0, v15, v16
	v_mov_b32_e32 v14, v1
	v_mov_b32_e32 v15, v1
	v_and_b32_e32 v184, 63, v12
	v_lshl_add_u64 v[180:181], s[12:13], 0, v[0:1]
	v_mov_b32_e32 v0, v1
	v_mov_b32_e32 v2, v1
	v_mov_b32_e32 v3, v1
	v_mov_b32_e32 v4, v1
	v_mov_b32_e32 v5, v1
	v_mov_b32_e32 v6, v1
	v_mov_b32_e32 v7, v1
	v_mov_b32_e32 v8, v1
	v_mov_b32_e32 v9, v1
	v_mov_b32_e32 v10, v1
	v_mov_b32_e32 v11, v1
	v_mov_b32_e32 v12, v1
	v_mov_b32_e32 v13, v1
	v_mov_b64_e32 v[64:65], v[14:15]
	v_mov_b64_e32 v[48:49], v[14:15]
	v_mov_b64_e32 v[32:33], v[14:15]
	v_mov_b64_e32 v[62:63], v[12:13]
	v_mov_b64_e32 v[60:61], v[10:11]
	v_mov_b64_e32 v[58:59], v[8:9]
	v_mov_b64_e32 v[56:57], v[6:7]
	v_mov_b64_e32 v[54:55], v[4:5]
	v_mov_b64_e32 v[52:53], v[2:3]
	v_mov_b64_e32 v[50:51], v[0:1]
	v_mov_b64_e32 v[46:47], v[12:13]
	v_mov_b64_e32 v[44:45], v[10:11]
	v_mov_b64_e32 v[42:43], v[8:9]
	v_mov_b64_e32 v[40:41], v[6:7]
	v_mov_b64_e32 v[38:39], v[4:5]
	v_mov_b64_e32 v[36:37], v[2:3]
	v_mov_b64_e32 v[34:35], v[0:1]
	v_mov_b64_e32 v[30:31], v[12:13]
	v_mov_b64_e32 v[28:29], v[10:11]
	v_mov_b64_e32 v[26:27], v[8:9]
	v_mov_b64_e32 v[24:25], v[6:7]
	v_mov_b64_e32 v[22:23], v[4:5]
	v_mov_b64_e32 v[20:21], v[2:3]
	v_mov_b64_e32 v[18:19], v[0:1]
	v_mov_b64_e32 v[16:17], v[14:15]
	s_lshl_b32 s29, s29, 8
	v_cmp_gt_u32_e64 s[40:41], 32, v184
	v_lshl_add_u32 v208, v183, 2, v187
	v_lshlrev_b32_e32 v207, 4, v175
	v_add_u32_e32 v176, 0x6000, v174
	v_mov_b32_e32 v209, 0
	s_mov_b32 s30, -1
	v_mov_b64_e32 v[14:15], v[12:13]
	v_mov_b64_e32 v[12:13], v[10:11]
	v_mov_b64_e32 v[10:11], v[8:9]
	v_mov_b64_e32 v[8:9], v[6:7]
	v_mov_b64_e32 v[6:7], v[4:5]
	v_mov_b64_e32 v[4:5], v[2:3]
	v_mov_b64_e32 v[2:3], v[0:1]
	v_add_u32_e32 v176, 0xffffe000, v176
	v_add_u32_e32 v178, 0xfffe0000, v178
	v_sub_f32_e32 v230, 0x40e00000, v217
	v_mov_b32_e32 v231, v230
	v_mov_b32_e32 v232, v230
	v_mov_b32_e32 v233, v230
	v_mov_b32_e32 v234, v230
	v_mov_b32_e32 v235, v230
	v_mov_b32_e32 v236, v230
	v_mov_b32_e32 v237, v230
	v_mov_b32_e32 v238, v230
	v_mov_b32_e32 v239, v230
	v_mov_b32_e32 v240, v230
	v_mov_b32_e32 v241, v230
	v_mov_b32_e32 v242, v230
	v_mov_b32_e32 v243, v230
	v_mov_b32_e32 v244, v230
	v_mov_b32_e32 v245, v230
	s_waitcnt lgkmcnt(0)
	s_barrier
.LBB0_1321:
	global_load_dwordx4 v[158:161], v176, s[18:19]
	global_load_dwordx4 v[162:165], v178, s[16:17]
	s_and_saveexec_b64 s[20:21], s[42:43]
	s_cbranch_execz .Lmla_A_nokr
	global_load_dwordx4 v[154:157], v[180:181], off
.Lmla_A_nokr:
	s_or_b64 exec, exec, s[20:21]
	ds_read_b128 v[114:117], v215 offset:24576
	ds_read_b128 v[118:121], v216 offset:24576
	ds_read_b128 v[222:225], v215 offset:28672
	ds_read_b128 v[226:229], v216 offset:28672
	v_add_u32_e32 v176, 0x2000, v176
	v_add_u32_e32 v178, 0x20000, v178
	s_mov_b64 s[20:21], 0x1000
	v_lshl_add_u64 v[180:181], v[180:181], 0, s[20:21]
	v_exp_f32_e32 v0, v82
	v_exp_f32_e32 v177, v83
	v_exp_f32_e32 v179, v84
	v_exp_f32_e32 v254, v85
	v_add_f32_e32 v219, v0, v177
	v_cvt_pk_fp8_f32 v246, v0, v177
	v_add_f32_e32 v219, v179, v219
	v_add_f32_e32 v219, v254, v219
	v_cvt_pk_fp8_f32 v246, v179, v254 op_sel:[0,0,1]
	s_waitcnt lgkmcnt(2)
	v_mfma_scale_f32_32x32x64_f8f6f4 v[114:129], v[114:121], v[146:153], v[230:245], v194, v193 op_sel_hi:[0,0,0]
	v_exp_f32_e32 v0, v86
	v_exp_f32_e32 v177, v87
	v_exp_f32_e32 v179, v88
	v_exp_f32_e32 v254, v89
	v_add_f32_e32 v219, v0, v219
	v_add_f32_e32 v219, v177, v219
	v_cvt_pk_fp8_f32 v247, v0, v177
	v_add_f32_e32 v219, v179, v219
	v_add_f32_e32 v219, v254, v219
	v_cvt_pk_fp8_f32 v247, v179, v254 op_sel:[0,0,1]
	ds_read_b128 v[82:85], v213 offset:24576
	ds_read_b128 v[86:89], v214 offset:24576
	s_waitcnt lgkmcnt(2)
	v_mfma_scale_f32_32x32x64_f8f6f4 v[98:113], v[222:229], v[146:153], v[230:245], v194, v193 op_sel_hi:[0,0,0]
	ds_read_b128 v[222:225], v213 offset:28672
	ds_read_b128 v[226:229], v214 offset:28672
	v_exp_f32_e32 v0, v90
	v_exp_f32_e32 v177, v91
	v_exp_f32_e32 v179, v92
	v_exp_f32_e32 v254, v93
	v_add_f32_e32 v219, v0, v219
	v_add_f32_e32 v219, v177, v219
	v_cvt_pk_fp8_f32 v248, v0, v177
	v_add_f32_e32 v219, v179, v219
	v_add_f32_e32 v219, v254, v219
	v_cvt_pk_fp8_f32 v248, v179, v254 op_sel:[0,0,1]
	v_exp_f32_e32 v0, v94
	v_exp_f32_e32 v177, v95
	v_exp_f32_e32 v179, v96
	v_exp_f32_e32 v254, v97
	v_add_f32_e32 v219, v0, v219
	v_add_f32_e32 v219, v177, v219
	v_cvt_pk_fp8_f32 v249, v0, v177
	v_add_f32_e32 v219, v179, v219
	v_add_f32_e32 v219, v254, v219
	v_cvt_pk_fp8_f32 v249, v179, v254 op_sel:[0,0,1]
	ds_read_b128 v[90:93], v185 offset:36864
	ds_read_b128 v[94:97], v186 offset:36864
	s_waitcnt lgkmcnt(4)
	v_mfma_scale_f32_32x32x64_f8f6f4 v[114:129], v[82:89], v[138:145], v[114:129], v194, v193 op_sel_hi:[0,0,0]
	v_exp_f32_e32 v0, v66
	v_exp_f32_e32 v177, v67
	v_exp_f32_e32 v179, v68
	v_exp_f32_e32 v254, v69
	v_add_f32_e32 v219, v0, v219
	v_add_f32_e32 v219, v177, v219
	v_cvt_pk_fp8_f32 v250, v0, v177
	v_add_f32_e32 v219, v179, v219
	v_add_f32_e32 v219, v254, v219
	v_cvt_pk_fp8_f32 v250, v179, v254 op_sel:[0,0,1]
	s_waitcnt lgkmcnt(2)
	v_mfma_scale_f32_32x32x64_f8f6f4 v[98:113], v[222:229], v[138:145], v[98:113], v194, v193 op_sel_hi:[0,0,0]
	ds_read_b128 v[222:225], v185 offset:38912
	ds_read_b128 v[226:229], v186 offset:38912
	v_exp_f32_e32 v0, v70
	v_exp_f32_e32 v177, v71
	v_exp_f32_e32 v179, v72
	v_exp_f32_e32 v254, v73
	v_add_f32_e32 v219, v0, v219
	v_add_f32_e32 v219, v177, v219
	v_cvt_pk_fp8_f32 v251, v0, v177
	v_add_f32_e32 v219, v179, v219
	v_add_f32_e32 v219, v254, v219
	v_cvt_pk_fp8_f32 v251, v179, v254 op_sel:[0,0,1]
	v_exp_f32_e32 v0, v74
	v_exp_f32_e32 v177, v75
	v_exp_f32_e32 v179, v76
	v_exp_f32_e32 v254, v77
	v_add_f32_e32 v219, v0, v219
	v_add_f32_e32 v219, v177, v219
	v_cvt_pk_fp8_f32 v252, v0, v177
	v_add_f32_e32 v219, v179, v219
	v_add_f32_e32 v219, v254, v219
	v_cvt_pk_fp8_f32 v252, v179, v254 op_sel:[0,0,1]
	s_waitcnt lgkmcnt(2)
; __device__ __forceinline__ void pv8(f32x16* o, const char* Vt, const v8i32 p8, int r32, int hi) {
;   const int sw = (r32 >> 2) & 3, a0 = r32 * 64 + (((hi * 2) ^ sw) << 4), a1 = r32 * 64 + (((hi * 2 + 1) ^ sw) << 4);
; #pragma unroll
;   for (int d0 = 0; d0 < 4; ++d0) {
;     const v8i32 vf = cat8(*reinterpret_cast<const v4i32*>(Vt + d0 * 2048 + a0), *reinterpret_cast<const v4i32*>(Vt + d0 * 2048 + a1));
;     o[d0] = __builtin_amdgcn_mfma_scale_f32_32x32x64_f8f6f4(p8, vf, o[d0], 0, 0, 0, 127, 0, 127); }
; }
; __device__ __forceinline__ void qkt9(f32x16& p0, f32x16& p1, const char* Kn, const char* Kr, const v8i32* qf, const float init, int r32, int hi) {
; #pragma unroll
;   for (int r = 0; r < 16; ++r) { p0[r] = init; p1[r] = init; }
; #pragma unroll
;   for (int s = 0; s < 2; ++s) { const int c0 = s * 4 + hi * 2;
;     const v8i32 a0 = cat8(*reinterpret_cast<const v4i32*>(Kn + KN8SW(r32, c0)), *reinterpret_cast<const v4i32*>(Kn + KN8SW(r32, c0 + 1)));
;     const v8i32 a1 = cat8(*reinterpret_cast<const v4i32*>(Kn + 4096 + KN8SW(r32, c0)), *reinterpret_cast<const v4i32*>(Kn + 4096 + KN8SW(r32, c0 + 1)));
;     p0 = __builtin_amdgcn_mfma_scale_f32_32x32x64_f8f6f4(a0, qf[s], p0, 0, 0, 0, 127, 0, 124);
;     p1 = __builtin_amdgcn_mfma_scale_f32_32x32x64_f8f6f4(a1, qf[s], p1, 0, 0, 0, 127, 0, 124); }
;   { const int c0 = hi * 2;
;     const v8i32 a0 = cat8(*reinterpret_cast<const v4i32*>(Kr + KR8SW(r32, c0)), *reinterpret_cast<const v4i32*>(Kr + KR8SW(r32, c0 + 1)));
;     const v8i32 a1 = cat8(*reinterpret_cast<const v4i32*>(Kr + 2048 + KR8SW(r32, c0)), *reinterpret_cast<const v4i32*>(Kr + 2048 + KR8SW(r32, c0 + 1)));
;     p0 = __builtin_amdgcn_mfma_scale_f32_32x32x64_f8f6f4(a0, qf[2], p0, 0, 0, 0, 127, 0, 124);
;     p1 = __builtin_amdgcn_mfma_scale_f32_32x32x64_f8f6f4(a1, qf[2], p1, 0, 0, 0, 127, 0, 124); }
; }
; __device__ __forceinline__ void attn_unit7(const unsigned char* __restrict__ Q8, int ldq, const unsigned char* __restrict__ Kn8, int ldk, const unsigned char* __restrict__ Kr8, ...
;     ...
;     pv8(o, Vt_lds, p8, r32, hi); partialSM9(pB0, pB1, m_reg, alB, thr_raw);
;     __syncthreads(); SWRITE(0);
;     RESC(alB); __syncthreads();
;     if (j + 2 < NT) SLOAD();
;     qkt9(pA0, pA1, Kn_lds, Kr_lds, qf, 7.0f - m_reg, r32, hi);
;     finishSM9(pB0, pB1, alB, l_reg, p8);
;     pv8(o, Vt_lds + 8192, p8, r32, hi); partialSM9(pA0, pA1, m_reg, alA, thr_raw);
	v_mfma_scale_f32_32x32x64_f8f6f4 v[114:129], v[90:97], v[130:137], v[114:129], v194, v193 op_sel_hi:[0,0,0]
	v_exp_f32_e32 v0, v78
	v_exp_f32_e32 v177, v79
	v_exp_f32_e32 v179, v80
	v_exp_f32_e32 v254, v81
	v_add_f32_e32 v219, v0, v219
	v_add_f32_e32 v219, v177, v219
	v_cvt_pk_fp8_f32 v253, v0, v177
	v_add_f32_e32 v219, v179, v219
	v_add_f32_e32 v219, v254, v219
	v_cvt_pk_fp8_f32 v253, v179, v254 op_sel:[0,0,1]
	ds_read_b128 v[90:93], v185 offset:0
	ds_read_b128 v[94:97], v186 offset:0
	ds_read_b128 v[82:85], v185 offset:2048
	ds_read_b128 v[86:89], v186 offset:2048
	ds_read_b128 v[74:77], v185 offset:4096
	ds_read_b128 v[78:81], v186 offset:4096
	ds_read_b128 v[66:69], v185 offset:6144
	ds_read_b128 v[70:73], v186 offset:6144
	s_waitcnt lgkmcnt(8)
	v_mfma_scale_f32_32x32x64_f8f6f4 v[98:113], v[222:229], v[130:137], v[98:113], v194, v193 op_sel_hi:[0,0,0]
	v_mov_b32_e32 v0, v219
	s_nop 1
	v_permlane32_swap_b32_e32 v219, v0
	v_add_f32_e32 v219, v219, v0
	v_fma_f32 v209, v209, v218, v219
	v_max_f32_e32 v177, v114, v115
	v_max3_f32 v177, v177, v116, v117
	v_max3_f32 v177, v177, v118, v119
	v_max3_f32 v177, v177, v120, v121
	v_max3_f32 v177, v177, v122, v123
	v_max3_f32 v177, v177, v124, v125
	v_max3_f32 v177, v177, v126, v127
	v_max3_f32 v177, v177, v128, v129
	s_waitcnt lgkmcnt(6)
	v_mfma_scale_f32_32x32x64_f8f6f4 v[50:65], v[246:253], v[90:97], v[50:65], v194, v194 op_sel_hi:[0,0,0]
	s_waitcnt lgkmcnt(4)
	v_mfma_scale_f32_32x32x64_f8f6f4 v[34:49], v[246:253], v[82:89], v[34:49], v194, v194 op_sel_hi:[0,0,0]
	s_waitcnt lgkmcnt(2)
	v_mfma_scale_f32_32x32x64_f8f6f4 v[18:33], v[246:253], v[74:81], v[18:33], v194, v194 op_sel_hi:[0,0,0]
	s_waitcnt lgkmcnt(0)
	v_mfma_scale_f32_32x32x64_f8f6f4 v[2:17], v[246:253], v[66:73], v[2:17], v194, v194 op_sel_hi:[0,0,0]
	v_max_f32_e32 v0, v98, v99
	v_max3_f32 v0, v0, v100, v101
	v_max3_f32 v0, v0, v102, v103
	v_max3_f32 v0, v0, v104, v105
	v_max3_f32 v0, v0, v106, v107
	v_max3_f32 v0, v0, v108, v109
	v_max3_f32 v0, v0, v110, v111
	v_max3_f32 v0, v0, v112, v113
	v_max_f32_e32 v177, v177, v0
	v_mov_b32_e32 v0, v177
	v_mov_b32_e32 v221, 1.0
	s_nop 0
	v_permlane32_swap_b32_e32 v177, v0
	v_max_f32_e32 v177, v177, v0
	v_cmp_ge_f32_e32 vcc, s90, v177
	s_cmp_eq_u64 vcc, exec
	s_cbranch_scc0 .Lmla_A_newmax
.Lmla_A_cont:
	v_cmp_gt_f32_e32 vcc, 1.0, v221
	s_barrier
	s_waitcnt vmcnt(0)
	ds_write_b128 v210, v[158:161]
	ds_write_b128 v211, v[162:165] offset:16384
	s_and_saveexec_b64 s[20:21], s[42:43]
	ds_write_b128 v212, v[154:157] offset:32768
	s_or_b64 exec, exec, s[20:21]
	s_cbranch_vccnz .Lmla_A_resc
.Lmla_A_resc_done:
	s_waitcnt lgkmcnt(0)
	s_barrier
	global_load_dwordx4 v[158:161], v176, s[18:19]
	global_load_dwordx4 v[162:165], v178, s[16:17]
	s_and_saveexec_b64 s[20:21], s[42:43]
	s_cbranch_execz .Lmla_B_nokr
	global_load_dwordx4 v[154:157], v[180:181], off
.Lmla_B_nokr:
	s_or_b64 exec, exec, s[20:21]
	ds_read_b128 v[82:85], v215 offset:16384
	ds_read_b128 v[86:89], v216 offset:16384
	ds_read_b128 v[222:225], v215 offset:20480
	ds_read_b128 v[226:229], v216 offset:20480
	v_add_u32_e32 v176, 0x2000, v176
	v_add_u32_e32 v178, 0x20000, v178
	s_mov_b64 s[20:21], 0x1000
	v_lshl_add_u64 v[180:181], v[180:181], 0, s[20:21]
	v_exp_f32_e32 v0, v114
	v_exp_f32_e32 v177, v115
	v_exp_f32_e32 v179, v116
	v_exp_f32_e32 v254, v117
	v_add_f32_e32 v219, v0, v177
	v_cvt_pk_fp8_f32 v246, v0, v177
	v_add_f32_e32 v219, v179, v219
	v_add_f32_e32 v219, v254, v219
	v_cvt_pk_fp8_f32 v246, v179, v254 op_sel:[0,0,1]
	s_waitcnt lgkmcnt(2)
	v_mfma_scale_f32_32x32x64_f8f6f4 v[82:97], v[82:89], v[146:153], v[230:245], v194, v193 op_sel_hi:[0,0,0]
	v_exp_f32_e32 v0, v118
	v_exp_f32_e32 v177, v119
	v_exp_f32_e32 v179, v120
	v_exp_f32_e32 v254, v121
	v_add_f32_e32 v219, v0, v219
	v_add_f32_e32 v219, v177, v219
	v_cvt_pk_fp8_f32 v247, v0, v177
	v_add_f32_e32 v219, v179, v219
	v_add_f32_e32 v219, v254, v219
	v_cvt_pk_fp8_f32 v247, v179, v254 op_sel:[0,0,1]
	ds_read_b128 v[114:117], v213 offset:16384
	ds_read_b128 v[118:121], v214 offset:16384
	s_waitcnt lgkmcnt(2)
	v_mfma_scale_f32_32x32x64_f8f6f4 v[66:81], v[222:229], v[146:153], v[230:245], v194, v193 op_sel_hi:[0,0,0]
	ds_read_b128 v[222:225], v213 offset:20480
	ds_read_b128 v[226:229], v214 offset:20480
	v_exp_f32_e32 v0, v122
	v_exp_f32_e32 v177, v123
	v_exp_f32_e32 v179, v124
	v_exp_f32_e32 v254, v125
	v_add_f32_e32 v219, v0, v219
	v_add_f32_e32 v219, v177, v219
	v_cvt_pk_fp8_f32 v248, v0, v177
	v_add_f32_e32 v219, v179, v219
	v_add_f32_e32 v219, v254, v219
	v_cvt_pk_fp8_f32 v248, v179, v254 op_sel:[0,0,1]
	v_exp_f32_e32 v0, v126
	v_exp_f32_e32 v177, v127
	v_exp_f32_e32 v179, v128
	v_exp_f32_e32 v254, v129
	v_add_f32_e32 v219, v0, v219
	v_add_f32_e32 v219, v177, v219
	v_cvt_pk_fp8_f32 v249, v0, v177
	v_add_f32_e32 v219, v179, v219
	v_add_f32_e32 v219, v254, v219
	v_cvt_pk_fp8_f32 v249, v179, v254 op_sel:[0,0,1]
	ds_read_b128 v[122:125], v185 offset:32768
	ds_read_b128 v[126:129], v186 offset:32768
	s_waitcnt lgkmcnt(4)
	v_mfma_scale_f32_32x32x64_f8f6f4 v[82:97], v[114:121], v[138:145], v[82:97], v194, v193 op_sel_hi:[0,0,0]
	v_exp_f32_e32 v0, v98
	v_exp_f32_e32 v177, v99
	v_exp_f32_e32 v179, v100
	v_exp_f32_e32 v254, v101
	v_add_f32_e32 v219, v0, v219
	v_add_f32_e32 v219, v177, v219
	v_cvt_pk_fp8_f32 v250, v0, v177
	v_add_f32_e32 v219, v179, v219
	v_add_f32_e32 v219, v254, v219
	v_cvt_pk_fp8_f32 v250, v179, v254 op_sel:[0,0,1]
	s_waitcnt lgkmcnt(2)
; #define SWRITE(b) do { *(bf16x8*)(V_lds + (b) * SHM_V + vst0) = vs0; *(bf16x8*)(V_lds + (b) * SHM_V + vst1) = vs1; const int kc = sc * 2;  \
;     *(bf16x8*)(K_lds + (b) * SHM_K + KSWZ(sr, kc)) = ks0; *(bf16x8*)(K_lds + (b) * SHM_K + KSWZ(32 + sr, kc)) = ks1; \
;     if constexpr (NR > 0) *(bf16x8*)(Kr_lds + (b) * SHM_KR + krst) = kr; } while (0)
; #define SWRITE(b) do { *(bf16x8*)(V_lds + (b) * SHM_V + vst0) = vs0; *(bf16x8*)(V_lds + (b) * SHM_V + vst0 + 8192) = vs1;  \
;     *(bf16x8*)(K_lds + (b) * SHM_K + kst0) = ks0; *(bf16x8*)(K_lds + (b) * SHM_K + kst0 + 8192) = ks1; \
;     if constexpr (NR > 0) *(bf16x8*)(Kr_lds + (b) * SHM_KR + krst) = kr; } while (0)
; #define RESC(a) do { if (__any((a) < 1.f)) { if (hi == 0) al_l[r32] = (a); asm volatile("s_waitcnt lgkmcnt(0)" ::: "memory"); \
;     _Pragma("unroll") for (int d = 0; d < 4; ++d) _Pragma("unroll") for (int r = 0; r < 16; ++r) o[d][r] *= al_l[crow(r, hi)]; } } while (0)
; #define SWRITE(b) do { *(bf16x8*)(V_lds + (b) * 16384 + vst0) = vs0; *(bf16x8*)(V_lds + (b) * 16384 + vst0 + 8192) = vs1;  \
;     *(v4i32*)(Kn_lds + (b) * 8192 + knst) = kn; if (krw) *(v4i32*)(Kr_lds + (b) * 4096 + krst) = kr; } while (0)
; #define RESC(a) do { if (__any((a) < 1.f)) { if (hi == 0) al_l[r32] = (a); asm volatile("s_waitcnt lgkmcnt(0)" ::: "memory"); \
;     _Pragma("unroll") for (int d = 0; d < 4; ++d) _Pragma("unroll") for (int r = 0; r < 16; ++r) o[d][r] *= al_l[crow(r, hi)]; } } while (0)
; __device__ __forceinline__ void partialSM9(f32x16& p0, f32x16& p1, float& m_run, float& alpha, const float thr2) {
;     ...
;     pmax = fmaxf(__uint_as_float(rr[0]), __uint_as_float(rr[1])); }
;   if (__builtin_expect(__all(pmax <= 7.0f + thr2), 1)) { alpha = 1.f; }
;   else { const float delta = fmaxf(pmax - 7.0f, 0.f); alpha = __builtin_amdgcn_exp2f(-delta); m_run += delta;
; #pragma unroll
;     for (int r = 0; r < 16; ++r) { p0[r] -= delta; p1[r] -= delta; } }
; }
; __device__ __forceinline__ void attn_unit7(const unsigned char* __restrict__ Q8, int ldq, const unsigned char* __restrict__ Kn8, int ldk, const unsigned char* __restrict__ Kr8, ...
;     ...
;     pv8(o, Vt_lds + 8192, p8, r32, hi); partialSM9(pA0, pA1, m_reg, alA, thr_raw);
;     __syncthreads(); if (j + 2 < NT) SWRITE(1);
;     RESC(alA); __syncthreads();
;   }
	v_mfma_scale_f32_32x32x64_f8f6f4 v[66:81], v[222:229], v[138:145], v[66:81], v194, v193 op_sel_hi:[0,0,0]
	ds_read_b128 v[222:225], v185 offset:34816
	ds_read_b128 v[226:229], v186 offset:34816
	v_exp_f32_e32 v0, v102
	v_exp_f32_e32 v177, v103
	v_exp_f32_e32 v179, v104
	v_exp_f32_e32 v254, v105
	v_add_f32_e32 v219, v0, v219
	v_add_f32_e32 v219, v177, v219
	v_cvt_pk_fp8_f32 v251, v0, v177
	v_add_f32_e32 v219, v179, v219
	v_add_f32_e32 v219, v254, v219
	v_cvt_pk_fp8_f32 v251, v179, v254 op_sel:[0,0,1]
	v_exp_f32_e32 v0, v106
	v_exp_f32_e32 v177, v107
	v_exp_f32_e32 v179, v108
	v_exp_f32_e32 v254, v109
	v_add_f32_e32 v219, v0, v219
	v_add_f32_e32 v219, v177, v219
	v_cvt_pk_fp8_f32 v252, v0, v177
	v_add_f32_e32 v219, v179, v219
	v_add_f32_e32 v219, v254, v219
	v_cvt_pk_fp8_f32 v252, v179, v254 op_sel:[0,0,1]
	s_waitcnt lgkmcnt(2)
	v_mfma_scale_f32_32x32x64_f8f6f4 v[82:97], v[122:129], v[130:137], v[82:97], v194, v193 op_sel_hi:[0,0,0]
	v_exp_f32_e32 v0, v110
	v_exp_f32_e32 v177, v111
	v_exp_f32_e32 v179, v112
	v_exp_f32_e32 v254, v113
	v_add_f32_e32 v219, v0, v219
	v_add_f32_e32 v219, v177, v219
	v_cvt_pk_fp8_f32 v253, v0, v177
	v_add_f32_e32 v219, v179, v219
	v_add_f32_e32 v219, v254, v219
	v_cvt_pk_fp8_f32 v253, v179, v254 op_sel:[0,0,1]
	ds_read_b128 v[122:125], v185 offset:8192
	ds_read_b128 v[126:129], v186 offset:8192
	ds_read_b128 v[114:117], v185 offset:10240
	ds_read_b128 v[118:121], v186 offset:10240
	ds_read_b128 v[106:109], v185 offset:12288
	ds_read_b128 v[110:113], v186 offset:12288
	ds_read_b128 v[98:101], v185 offset:14336
	ds_read_b128 v[102:105], v186 offset:14336
	s_waitcnt lgkmcnt(8)
	v_mfma_scale_f32_32x32x64_f8f6f4 v[66:81], v[222:229], v[130:137], v[66:81], v194, v193 op_sel_hi:[0,0,0]
	v_mov_b32_e32 v0, v219
	s_nop 1
	v_permlane32_swap_b32_e32 v219, v0
	v_add_f32_e32 v219, v219, v0
	v_fma_f32 v209, v209, v221, v219
	v_max_f32_e32 v177, v82, v83
	v_max3_f32 v177, v177, v84, v85
	v_max3_f32 v177, v177, v86, v87
	v_max3_f32 v177, v177, v88, v89
	v_max3_f32 v177, v177, v90, v91
	v_max3_f32 v177, v177, v92, v93
	v_max3_f32 v177, v177, v94, v95
	v_max3_f32 v177, v177, v96, v97
	s_waitcnt lgkmcnt(6)
	v_mfma_scale_f32_32x32x64_f8f6f4 v[50:65], v[246:253], v[122:129], v[50:65], v194, v194 op_sel_hi:[0,0,0]
	s_waitcnt lgkmcnt(4)
	v_mfma_scale_f32_32x32x64_f8f6f4 v[34:49], v[246:253], v[114:121], v[34:49], v194, v194 op_sel_hi:[0,0,0]
	s_waitcnt lgkmcnt(2)
	v_mfma_scale_f32_32x32x64_f8f6f4 v[18:33], v[246:253], v[106:113], v[18:33], v194, v194 op_sel_hi:[0,0,0]
	s_waitcnt lgkmcnt(0)
	v_mfma_scale_f32_32x32x64_f8f6f4 v[2:17], v[246:253], v[98:105], v[2:17], v194, v194 op_sel_hi:[0,0,0]
	v_max_f32_e32 v0, v66, v67
	v_max3_f32 v0, v0, v68, v69
	v_max3_f32 v0, v0, v70, v71
	v_max3_f32 v0, v0, v72, v73
	v_max3_f32 v0, v0, v74, v75
	v_max3_f32 v0, v0, v76, v77
	v_max3_f32 v0, v0, v78, v79
	v_max3_f32 v0, v0, v80, v81
	v_max_f32_e32 v177, v177, v0
	v_mov_b32_e32 v0, v177
	v_mov_b32_e32 v218, 1.0
	s_nop 0
	v_permlane32_swap_b32_e32 v177, v0
	v_max_f32_e32 v177, v177, v0
	v_cmp_ge_f32_e32 vcc, s90, v177
	s_cmp_eq_u64 vcc, exec
	s_cbranch_scc0 .Lmla_B_newmax
.Lmla_B_cont:
	v_cmp_gt_f32_e32 vcc, 1.0, v218
	s_barrier
	s_waitcnt vmcnt(0)
	ds_write_b128 v210, v[158:161] offset:8192
	ds_write_b128 v211, v[162:165] offset:24576
	s_and_saveexec_b64 s[20:21], s[42:43]
	ds_write_b128 v212, v[154:157] offset:36864
	s_or_b64 exec, exec, s[20:21]
	s_cbranch_vccnz .Lmla_B_resc
.Lmla_B_resc_done:
	s_add_i32 s30, s30, 2
	v_mov_b32_e32 v0, v218
	s_waitcnt lgkmcnt(0)
	s_barrier
	s_cmpk_gt_u32 s30, 0xfc
	s_cbranch_scc0 .LBB0_1321
	s_branch .LBB0_1343
.Lmla_A_newmax:
	v_add_f32_e32 v0, 0xc0e00000, v177
	v_max_f32_e32 v177, 0, v0
	v_exp_f32_e64 v221, -v177
	v_add_f32_e32 v217, v217, v177
	v_sub_f32_e32 v129, v129, v177
	v_sub_f32_e32 v128, v128, v177
	v_sub_f32_e32 v127, v127, v177
	v_sub_f32_e32 v126, v126, v177
	v_sub_f32_e32 v125, v125, v177
	v_sub_f32_e32 v124, v124, v177
	v_sub_f32_e32 v123, v123, v177
	v_sub_f32_e32 v122, v122, v177
	v_sub_f32_e32 v121, v121, v177
	v_sub_f32_e32 v120, v120, v177
	v_sub_f32_e32 v119, v119, v177
	v_sub_f32_e32 v118, v118, v177
	v_sub_f32_e32 v117, v117, v177
	v_sub_f32_e32 v116, v116, v177
	v_sub_f32_e32 v115, v115, v177
	v_sub_f32_e32 v114, v114, v177
	v_sub_f32_e32 v113, v113, v177
	v_sub_f32_e32 v112, v112, v177
	v_sub_f32_e32 v111, v111, v177
	v_sub_f32_e32 v110, v110, v177
	v_sub_f32_e32 v109, v109, v177
	v_sub_f32_e32 v108, v108, v177
	v_sub_f32_e32 v107, v107, v177
	v_sub_f32_e32 v106, v106, v177
	v_sub_f32_e32 v105, v105, v177
	v_sub_f32_e32 v104, v104, v177
	v_sub_f32_e32 v103, v103, v177
	v_sub_f32_e32 v102, v102, v177
	v_sub_f32_e32 v101, v101, v177
	v_sub_f32_e32 v100, v100, v177
	v_sub_f32_e32 v99, v99, v177
	v_sub_f32_e32 v98, v98, v177
	v_sub_f32_e32 v230, 0x40e00000, v217
	v_mov_b32_e32 v231, v230
	v_mov_b32_e32 v232, v230
	v_mov_b32_e32 v233, v230
	v_mov_b32_e32 v234, v230
	v_mov_b32_e32 v235, v230
	v_mov_b32_e32 v236, v230
	v_mov_b32_e32 v237, v230
	v_mov_b32_e32 v238, v230
	v_mov_b32_e32 v239, v230
	v_mov_b32_e32 v240, v230
	v_mov_b32_e32 v241, v230
	v_mov_b32_e32 v242, v230
	v_mov_b32_e32 v243, v230
	v_mov_b32_e32 v244, v230
	v_mov_b32_e32 v245, v230
	s_branch .Lmla_A_cont
; __device__ __forceinline__ void partialSM9(f32x16& p0, f32x16& p1, float& m_run, float& alpha, const float thr2) {
;     ...
;     pmax = fmaxf(__uint_as_float(rr[0]), __uint_as_float(rr[1])); }
;   if (__builtin_expect(__all(pmax <= 7.0f + thr2), 1)) { alpha = 1.f; }
;   else { const float delta = fmaxf(pmax - 7.0f, 0.f); alpha = __builtin_amdgcn_exp2f(-delta); m_run += delta;
; #pragma unroll
;     for (int r = 0; r < 16; ++r) { p0[r] -= delta; p1[r] -= delta; } }
; }
.Lmla_A_resc:
	s_and_saveexec_b64 s[20:21], s[40:41]
	ds_write_b32 v208, v221 offset:41088
	s_or_b64 exec, exec, s[20:21]
	v_add_u32_e32 v0, v187, v207
	s_waitcnt lgkmcnt(0)
	ds_read_b128 v[66:69], v0 offset:41184
	ds_read_b128 v[70:73], v0 offset:41152
	ds_read_b128 v[74:77], v0 offset:41120
	ds_read_b128 v[78:81], v0 offset:41088
	s_nop 15
	s_nop 7
	s_waitcnt lgkmcnt(0)
	v_pk_mul_f32 v[62:63], v[62:63], v[66:67]
	v_pk_mul_f32 v[58:59], v[58:59], v[70:71]
	v_pk_mul_f32 v[54:55], v[54:55], v[74:75]
	v_pk_mul_f32 v[64:65], v[64:65], v[68:69]
	v_pk_mul_f32 v[60:61], v[60:61], v[72:73]
	v_pk_mul_f32 v[56:57], v[56:57], v[76:77]
	v_pk_mul_f32 v[52:53], v[52:53], v[80:81]
	v_pk_mul_f32 v[50:51], v[50:51], v[78:79]
	v_pk_mul_f32 v[46:47], v[46:47], v[66:67]
	v_pk_mul_f32 v[42:43], v[42:43], v[70:71]
	v_pk_mul_f32 v[38:39], v[38:39], v[74:75]
	v_pk_mul_f32 v[48:49], v[48:49], v[68:69]
	v_pk_mul_f32 v[44:45], v[44:45], v[72:73]
	v_pk_mul_f32 v[40:41], v[40:41], v[76:77]
	v_pk_mul_f32 v[36:37], v[36:37], v[80:81]
	v_pk_mul_f32 v[34:35], v[34:35], v[78:79]
	v_pk_mul_f32 v[30:31], v[30:31], v[66:67]
	v_pk_mul_f32 v[26:27], v[26:27], v[70:71]
	v_pk_mul_f32 v[22:23], v[22:23], v[74:75]
	v_pk_mul_f32 v[32:33], v[32:33], v[68:69]
	v_pk_mul_f32 v[28:29], v[28:29], v[72:73]
	v_pk_mul_f32 v[24:25], v[24:25], v[76:77]
	v_pk_mul_f32 v[20:21], v[20:21], v[80:81]
	v_pk_mul_f32 v[18:19], v[18:19], v[78:79]
	v_pk_mul_f32 v[14:15], v[14:15], v[66:67]
	v_pk_mul_f32 v[10:11], v[10:11], v[70:71]
	v_pk_mul_f32 v[6:7], v[6:7], v[74:75]
	v_pk_mul_f32 v[16:17], v[16:17], v[68:69]
	v_pk_mul_f32 v[12:13], v[12:13], v[72:73]
	v_pk_mul_f32 v[8:9], v[8:9], v[76:77]
	v_pk_mul_f32 v[4:5], v[4:5], v[80:81]
	v_pk_mul_f32 v[2:3], v[2:3], v[78:79]
	s_branch .Lmla_A_resc_done
.Lmla_B_newmax:
	v_add_f32_e32 v0, 0xc0e00000, v177
	v_max_f32_e32 v177, 0, v0
	v_exp_f32_e64 v218, -v177
	v_add_f32_e32 v217, v217, v177
	v_sub_f32_e32 v97, v97, v177
	v_sub_f32_e32 v96, v96, v177
	v_sub_f32_e32 v95, v95, v177
	v_sub_f32_e32 v94, v94, v177
	v_sub_f32_e32 v93, v93, v177
	v_sub_f32_e32 v92, v92, v177
	v_sub_f32_e32 v91, v91, v177
	v_sub_f32_e32 v90, v90, v177
	v_sub_f32_e32 v89, v89, v177
	v_sub_f32_e32 v88, v88, v177
	v_sub_f32_e32 v87, v87, v177
	v_sub_f32_e32 v86, v86, v177
	v_sub_f32_e32 v85, v85, v177
	v_sub_f32_e32 v84, v84, v177
	v_sub_f32_e32 v83, v83, v177
	v_sub_f32_e32 v82, v82, v177
	v_sub_f32_e32 v81, v81, v177
	v_sub_f32_e32 v80, v80, v177
	v_sub_f32_e32 v79, v79, v177
	v_sub_f32_e32 v78, v78, v177
	v_sub_f32_e32 v77, v77, v177
	v_sub_f32_e32 v76, v76, v177
	v_sub_f32_e32 v75, v75, v177
	v_sub_f32_e32 v74, v74, v177
	v_sub_f32_e32 v73, v73, v177
	v_sub_f32_e32 v72, v72, v177
	v_sub_f32_e32 v71, v71, v177
	v_sub_f32_e32 v70, v70, v177
	v_sub_f32_e32 v69, v69, v177
	v_sub_f32_e32 v68, v68, v177
	v_sub_f32_e32 v67, v67, v177
	v_sub_f32_e32 v66, v66, v177
	v_sub_f32_e32 v230, 0x40e00000, v217
	v_mov_b32_e32 v231, v230
	v_mov_b32_e32 v232, v230
	v_mov_b32_e32 v233, v230
	v_mov_b32_e32 v234, v230
	v_mov_b32_e32 v235, v230
	v_mov_b32_e32 v236, v230
	v_mov_b32_e32 v237, v230
	v_mov_b32_e32 v238, v230
	v_mov_b32_e32 v239, v230
	v_mov_b32_e32 v240, v230
	v_mov_b32_e32 v241, v230
	v_mov_b32_e32 v242, v230
	v_mov_b32_e32 v243, v230
	v_mov_b32_e32 v244, v230
	v_mov_b32_e32 v245, v230
	s_branch .Lmla_B_cont
.Lmla_B_resc:
	s_and_saveexec_b64 s[20:21], s[40:41]
	ds_write_b32 v208, v218 offset:41088
	s_or_b64 exec, exec, s[20:21]
	v_add_u32_e32 v0, v187, v207
	s_waitcnt lgkmcnt(0)
	ds_read_b128 v[98:101], v0 offset:41184
	ds_read_b128 v[102:105], v0 offset:41152
	ds_read_b128 v[106:109], v0 offset:41120
	ds_read_b128 v[110:113], v0 offset:41088
	s_nop 15
	s_nop 7
	s_waitcnt lgkmcnt(0)
	v_pk_mul_f32 v[62:63], v[62:63], v[98:99]
	v_pk_mul_f32 v[58:59], v[58:59], v[102:103]
	v_pk_mul_f32 v[54:55], v[54:55], v[106:107]
	v_pk_mul_f32 v[64:65], v[64:65], v[100:101]
	v_pk_mul_f32 v[60:61], v[60:61], v[104:105]
	v_pk_mul_f32 v[56:57], v[56:57], v[108:109]
	v_pk_mul_f32 v[52:53], v[52:53], v[112:113]
	v_pk_mul_f32 v[50:51], v[50:51], v[110:111]
	v_pk_mul_f32 v[46:47], v[46:47], v[98:99]
	v_pk_mul_f32 v[42:43], v[42:43], v[102:103]
	v_pk_mul_f32 v[38:39], v[38:39], v[106:107]
	v_pk_mul_f32 v[48:49], v[48:49], v[100:101]
	v_pk_mul_f32 v[44:45], v[44:45], v[104:105]
	v_pk_mul_f32 v[40:41], v[40:41], v[108:109]
	v_pk_mul_f32 v[36:37], v[36:37], v[112:113]
	v_pk_mul_f32 v[34:35], v[34:35], v[110:111]
	v_pk_mul_f32 v[30:31], v[30:31], v[98:99]
	v_pk_mul_f32 v[26:27], v[26:27], v[102:103]
	v_pk_mul_f32 v[22:23], v[22:23], v[106:107]
	v_pk_mul_f32 v[32:33], v[32:33], v[100:101]
	v_pk_mul_f32 v[28:29], v[28:29], v[104:105]
	v_pk_mul_f32 v[24:25], v[24:25], v[108:109]
	v_pk_mul_f32 v[20:21], v[20:21], v[112:113]
	v_pk_mul_f32 v[18:19], v[18:19], v[110:111]
	v_pk_mul_f32 v[14:15], v[14:15], v[98:99]
	v_pk_mul_f32 v[10:11], v[10:11], v[102:103]
	v_pk_mul_f32 v[6:7], v[6:7], v[106:107]
	v_pk_mul_f32 v[16:17], v[16:17], v[100:101]
	v_pk_mul_f32 v[12:13], v[12:13], v[104:105]
	v_pk_mul_f32 v[8:9], v[8:9], v[108:109]
	v_pk_mul_f32 v[4:5], v[4:5], v[112:113]
	v_pk_mul_f32 v[2:3], v[2:3], v[110:111]
	s_branch .Lmla_B_resc_done
